# grid-barrier seams: L1 invalidate issued right after the arrival atomic (overlaps the wait) instead of after the release is observed
# speedup vs baseline: 1.0086x; 1.0042x over previous
; __device__ __forceinline__ unsigned xb_ld(unsigned* p)              { return __hip_atomic_load(p, __ATOMIC_RELAXED, __HIP_MEMORY_SCOPE_AGENT); }
; __device__ __forceinline__ unsigned xb_add(unsigned* p, unsigned v) { return __hip_atomic_fetch_add(p, v, __ATOMIC_RELAXED, __HIP_MEMORY_SCOPE_AGENT); }
; #define XB_SPIN(cond, bar) do { unsigned _sp = 0; while (cond) { __builtin_amdgcn_s_sleep(1); \
;     if ((++_sp & 255u) == 0u) { if (xb_ld(&(bar)[XB_TMO])) break; if (_sp > XB_SPIN_CAP) { atomicAdd(&(bar)[XB_TMO], 1u); break; } } } } while (0)
; __device__ __forceinline__ void xcd_barrier(const XcdBarrier& b) {
;     ...
;     if (threadIdx.x == 0) {
;         unsigned* bar = b.bar;
;         __builtin_amdgcn_s_waitcnt(0);
;         unsigned nloc = b.st[0], nx = b.st[1];
;         if (nloc == 0u) { xcd_barrier_complete(bar, b.x, nloc, nx); b.st[0] = nloc; b.st[1] = nx; }
;         const unsigned old = xb_add(&bar[XB_XSUB(b.x)], 1u);
;         const unsigned gen = old / nloc;
;         if (old + 1u == (gen + 1u) * nloc) {
;             __builtin_amdgcn_fence(__ATOMIC_RELEASE, "agent");
;             asm volatile("s_waitcnt vmcnt(0)" ::: "memory");
;             const unsigned og = xb_add(&bar[XB_TOP], 1u);
;             const unsigned tg = og / nx;
;             if (og + 1u == (tg + 1u) * nx) xb_add(&bar[XB_TOPGEN], 1u);
;             else XB_SPIN(xb_ld(&bar[XB_TOPGEN]) == tg, bar);
;             __builtin_amdgcn_fence(__ATOMIC_ACQUIRE, "agent");
;             xb_add(&bar[XB_XGEN(b.x)], 1u);
;             asm volatile("s_waitcnt vmcnt(0)" ::: "memory");
;         } else {
;             XB_SPIN(xb_ld(&bar[XB_XGEN(b.x)]) == gen, bar);
;             __builtin_amdgcn_fence(__ATOMIC_ACQUIRE, "agent");
;             asm volatile("s_waitcnt vmcnt(0)" ::: "memory");
.LBB0_63:
	s_or_b64 exec, exec, s[8:9]
	v_cvt_f32_u32_e32 v4, v2
	s_waitcnt vmcnt(0)
	buffer_inv sc1
	v_readfirstlane_b32 s6, v3
	v_sub_u32_e32 v3, 0, v2
	v_rcp_iflag_f32_e32 v4, v4
	v_add_u32_e32 v5, s6, v1
	v_mul_f32_e32 v4, 0x4f7ffffe, v4
	v_cvt_u32_f32_e32 v4, v4
	v_mul_lo_u32 v1, v3, v4
	v_mul_hi_u32 v1, v4, v1
	v_add_u32_e32 v1, v4, v1
	v_mul_hi_u32 v1, v5, v1
	v_mul_lo_u32 v3, v1, v2
	v_sub_u32_e32 v3, v5, v3
	v_add_u32_e32 v4, 1, v1
	v_cmp_ge_u32_e32 vcc, v3, v2
	s_nop 1
	v_cndmask_b32_e32 v1, v1, v4, vcc
	v_sub_u32_e32 v4, v3, v2
	v_cndmask_b32_e32 v3, v3, v4, vcc
	v_add_u32_e32 v4, 1, v1
	v_cmp_ge_u32_e32 vcc, v3, v2
	v_add_u32_e32 v3, 1, v5
	s_nop 0
	v_cndmask_b32_e32 v1, v1, v4, vcc
	v_mul_lo_u32 v4, v2, v1
	v_add_u32_e32 v2, v4, v2
	v_cmp_ne_u32_e32 vcc, v3, v2
	s_and_saveexec_b64 s[6:7], vcc
	s_xor_b64 s[6:7], exec, s[6:7]
	s_cbranch_execz .LBB0_77
	s_waitcnt lgkmcnt(0)
	v_mov_b32_e32 v0, 0x2000
	global_load_dword v0, v0, s[4:5] offset:1024 sc1
	s_add_u32 s12, s4, 0x2400
	s_addc_u32 s13, s5, 0
	s_waitcnt vmcnt(0)
	v_cmp_eq_u32_e32 vcc, v0, v1
	s_and_saveexec_b64 s[8:9], vcc
	s_cbranch_execz .LBB0_76
	s_add_u32 s10, s92, 0x1ef00200
	s_addc_u32 s11, s93, 0
	s_mov_b32 s24, 1
	s_mov_b64 s[14:15], 0
	v_mov_b32_e32 v0, 0
	s_branch .LBB0_67

; __device__ __forceinline__ unsigned xb_ld(unsigned* p)              { return __hip_atomic_load(p, __ATOMIC_RELAXED, __HIP_MEMORY_SCOPE_AGENT); }
; #define XB_SPIN(cond, bar) do { unsigned _sp = 0; while (cond) { __builtin_amdgcn_s_sleep(1); \
;     if ((++_sp & 255u) == 0u) { if (xb_ld(&(bar)[XB_TMO])) break; if (_sp > XB_SPIN_CAP) { atomicAdd(&(bar)[XB_TMO], 1u); break; } } } } while (0)
; __device__ __forceinline__ void xcd_barrier(const XcdBarrier& b) {
;     ...
;             XB_SPIN(xb_ld(&bar[XB_XGEN(b.x)]) == gen, bar);
;             __builtin_amdgcn_fence(__ATOMIC_ACQUIRE, "agent");
;             asm volatile("s_waitcnt vmcnt(0)" ::: "memory");
.LBB0_76:
	s_or_b64 exec, exec, s[8:9]
	s_waitcnt vmcnt(0)
	s_waitcnt vmcnt(0)

; __device__ __forceinline__ unsigned xb_ld(unsigned* p)              { return __hip_atomic_load(p, __ATOMIC_RELAXED, __HIP_MEMORY_SCOPE_AGENT); }
; __device__ __forceinline__ unsigned xb_add(unsigned* p, unsigned v) { return __hip_atomic_fetch_add(p, v, __ATOMIC_RELAXED, __HIP_MEMORY_SCOPE_AGENT); }
; #define XB_SPIN(cond, bar) do { unsigned _sp = 0; while (cond) { __builtin_amdgcn_s_sleep(1); \
;     if ((++_sp & 255u) == 0u) { if (xb_ld(&(bar)[XB_TMO])) break; if (_sp > XB_SPIN_CAP) { atomicAdd(&(bar)[XB_TMO], 1u); break; } } } } while (0)
; __device__ __forceinline__ void xcd_barrier(const XcdBarrier& b) {
;     ...
;             const unsigned og = xb_add(&bar[XB_TOP], 1u);
;             const unsigned tg = og / nx;
;             if (og + 1u == (tg + 1u) * nx) xb_add(&bar[XB_TOPGEN], 1u);
;             else XB_SPIN(xb_ld(&bar[XB_TOPGEN]) == tg, bar);
;             __builtin_amdgcn_fence(__ATOMIC_ACQUIRE, "agent");
;             xb_add(&bar[XB_XGEN(b.x)], 1u);
.LBB0_94:
	s_or_b64 exec, exec, s[6:7]
	s_mov_b64 s[6:7], exec
	v_mbcnt_lo_u32_b32 v0, s6, 0
	v_mbcnt_hi_u32_b32 v0, s7, v0
	v_cmp_eq_u32_e32 vcc, 0, v0
	s_waitcnt vmcnt(0)
	s_and_saveexec_b64 s[8:9], vcc
	s_cbranch_execz .LBB0_96
	s_bcnt1_i32_b64 s6, s[6:7]
	v_mov_b32_e32 v0, 0x2000
	v_mov_b32_e32 v1, s6
	global_atomic_add v0, v1, s[4:5] offset:1024
